# v25 + grid barrier: the first workgroup of each XCD to arrive starts an L2 writeback early (in addition to the last arriver's)
# baseline (speedup 1.0000x reference)
.LBB0_199:
	s_or_b64 exec, exec, s[4:5]
	v_cvt_f32_u32_e32 v4, v2
	s_waitcnt vmcnt(0)
	v_readfirstlane_b32 s4, v3
	v_sub_u32_e32 v3, 0, v2
	v_rcp_iflag_f32_e32 v4, v4
	v_add_u32_e32 v5, s4, v1
	v_mul_f32_e32 v4, 0x4f7ffffe, v4
	v_cvt_u32_f32_e32 v4, v4
	v_mul_lo_u32 v1, v3, v4
	v_mul_hi_u32 v1, v4, v1
	v_add_u32_e32 v1, v4, v1
	v_mul_hi_u32 v1, v5, v1
	v_mul_lo_u32 v3, v1, v2
	v_sub_u32_e32 v3, v5, v3
	v_add_u32_e32 v4, 1, v1
	v_cmp_ge_u32_e32 vcc, v3, v2
	s_nop 1
	v_cndmask_b32_e32 v1, v1, v4, vcc
	v_sub_u32_e32 v4, v3, v2
	v_cndmask_b32_e32 v3, v3, v4, vcc
	v_add_u32_e32 v4, 1, v1
	v_cmp_ge_u32_e32 vcc, v3, v2
	v_add_u32_e32 v3, 1, v5
	s_nop 0
	v_cndmask_b32_e32 v1, v1, v4, vcc
	v_mul_lo_u32 v4, v2, v1
	v_add_u32_e32 v2, v4, v2
	v_cmp_ne_u32_e32 vcc, v3, v2
	s_and_saveexec_b64 s[4:5], vcc
	s_xor_b64 s[4:5], exec, s[4:5]
	s_cbranch_execz .LBB0_213
	v_sub_u32_e32 v4, v3, v4
	s_nop 0
	v_readfirstlane_b32 s98, v4
	s_cmp_eq_u32 s98, 1
	s_cbranch_scc0 .Lewb_0
	buffer_wbl2 sc1
.Lewb_0:
	v_readlane_b32 s8, v242, 40
	v_readlane_b32 s9, v242, 41
	s_waitcnt lgkmcnt(0)
	s_nop 3
	global_load_dword v0, v173, s[8:9] sc1
	s_waitcnt vmcnt(0)
	v_cmp_eq_u32_e32 vcc, v0, v1
	s_and_saveexec_b64 s[8:9], vcc
	s_cbranch_execz .LBB0_212
	s_mov_b32 s11, 1
	s_mov_b64 s[28:29], 0
	s_branch .LBB0_203

.Lewb_4:
	v_readlane_b32 s8, v242, 40
	v_readlane_b32 s9, v242, 41
	s_waitcnt lgkmcnt(0)
	s_nop 3
	global_load_dword v0, v173, s[8:9] sc1
	s_waitcnt vmcnt(0)
	v_cmp_eq_u32_e32 vcc, v0, v1
	s_and_saveexec_b64 s[8:9], vcc
	s_cbranch_execz .LBB0_1063
	s_mov_b32 s26, 1
	s_mov_b64 s[28:29], 0
	s_branch .LBB0_1054

.Lewb_6:
	v_readlane_b32 s8, v242, 40
	v_readlane_b32 s9, v242, 41
	s_waitcnt lgkmcnt(0)
	s_nop 3
	global_load_dword v0, v173, s[8:9] sc1
	s_waitcnt vmcnt(0)
	v_cmp_eq_u32_e32 vcc, v0, v1
	s_and_saveexec_b64 s[8:9], vcc
	s_cbranch_execz .LBB0_1192
	s_mov_b32 s26, 1
	s_mov_b64 s[40:41], 0
	s_branch .LBB0_1183
